# LDS fragment reads software-pipelined in MLA flash and NA loops (renamed into free VGPRs, counted lgkmcnt); NA bias lookup de-serialized
# speedup vs baseline: 1.0344x; 1.0109x over previous
; __device__ __forceinline__ unsigned cvt_pk_bf16(float lo, float hi) { const f32x2c f = {lo, hi}; return __builtin_bit_cast(unsigned, __builtin_convertvector(f, bf16x2c)); }
; #define LASP __attribute__((address_space(3)))
; template <int DQK>
; __device__ __forceinline__ void flash_item(unsigned char* smem, const bf16_t* Q, int qs, const bf16_t* K0, const bf16_t* V0, int n0, const bf16_t* K1, const bf16_t* V1, int n1, int ks, int vs, bf16_t* Oo, int os, float shift) {
;     ...
;         for (int qg = 0; qg < 2; ++qg) {
;             float ps = 0.f;
; #pragma unroll
;             for (int kg = 0; kg < NKG; ++kg)
; #pragma unroll
;                 for (int j = 0; j < 4; ++j) { const float p = __builtin_amdgcn_exp2f(s[kg][qg][j]); s[kg][qg][j] = p; ps += p; }
;             lsum[qg] += ps;
;         }
; #pragma unroll
;         for (int kp = 0; kp < NKP; ++kp) {
;             bf16x8_t pb[2];
; #pragma unroll
;             for (int qg = 0; qg < 2; ++qg) {
;                 const f32x4_t a = s[2 * kp][qg], b = s[2 * kp + 1][qg];
;                 u32x4_t pk; pk.x = pg8::cvt_pk_bf16(a[0], a[1]); pk.y = pg8::cvt_pk_bf16(a[2], a[3]); pk.z = pg8::cvt_pk_bf16(b[0], b[1]); pk.w = pg8::cvt_pk_bf16(b[2], b[3]);
;                 pb[qg] = __builtin_bit_cast(bf16x8_t, pk);
;             }
; #pragma unroll
;             for (int dg = 0; dg < 4; ++dg) {
;                 LASP unsigned char* va = ls + VOFF + (32 * kp + 4 * fq + (fr >> 2)) * VR + (16 * dg + 4 * (fr & 3)) * 2;
;                 const s16x4 v0 = __builtin_amdgcn_ds_read_tr16_b64_v4i16((LASP s16x4*)va);
;                 const s16x4 v1 = __builtin_amdgcn_ds_read_tr16_b64_v4i16((LASP s16x4*)(va + 16 * VR));
;                 const bf16x8_t vf = __builtin_shufflevector(v0, v1, 0, 1, 2, 3, 4, 5, 6, 7);
;                 o[dg][0] = __builtin_amdgcn_mfma_f32_16x16x32_bf16(vf, pb[0], o[dg][0], 0, 0, 0);
;                 o[dg][1] = __builtin_amdgcn_mfma_f32_16x16x32_bf16(vf, pb[1], o[dg][1], 0, 0, 0);
;             }
;         }
.LBB0_831:
	ds_read_b64_tr_b16 v[182:183], v163 offset:35072
	ds_read_b64_tr_b16 v[180:181], v163 offset:32768
	ds_read_b64_tr_b16 v[184:185], v163 offset:32832
	ds_read_b64_tr_b16 v[186:187], v163 offset:35136
	ds_read_b64_tr_b16 v[188:189], v163 offset:32864
	ds_read_b64_tr_b16 v[190:191], v163 offset:35168
	ds_read_b64_tr_b16 v[192:193], v163 offset:32800
	ds_read_b64_tr_b16 v[194:195], v163 offset:35104
	ds_read_b64_tr_b16 v[196:197], v163 offset:37376
	ds_read_b64_tr_b16 v[198:199], v163 offset:39680
	ds_read_b64_tr_b16 v[200:201], v163 offset:37408
	ds_read_b64_tr_b16 v[202:203], v163 offset:39712
	s_nop 0
	v_exp_f32_e32 v148, v138
	v_exp_f32_e32 v149, v139
	v_exp_f32_e32 v150, v140
	v_exp_f32_e32 v151, v141
	v_add_f32_e32 v138, 0, v148
	v_exp_f32_e32 v152, v134
	v_add_f32_e32 v138, v149, v138
	v_exp_f32_e32 v153, v135
	v_add_f32_e32 v138, v150, v138
	v_exp_f32_e32 v166, v136
	v_add_f32_e32 v138, v151, v138
	v_exp_f32_e32 v167, v137
	v_add_f32_e32 v134, v152, v138
	v_exp_f32_e32 v136, v130
	v_add_f32_e32 v134, v153, v134
	v_exp_f32_e32 v137, v131
	v_add_f32_e32 v134, v166, v134
	v_exp_f32_e32 v138, v132
	v_add_f32_e32 v134, v167, v134
	v_exp_f32_e32 v139, v133
	v_add_f32_e32 v130, v136, v134
	v_exp_f32_e32 v140, v126
	v_add_f32_e32 v130, v137, v130
	v_exp_f32_e32 v141, v127
	v_add_f32_e32 v130, v138, v130
	v_exp_f32_e32 v164, v128
	v_add_f32_e32 v130, v139, v130
	v_exp_f32_e32 v165, v129
	v_add_f32_e32 v126, v140, v130
	v_exp_f32_e32 v130, v110
	v_add_f32_e32 v126, v141, v126
	v_exp_f32_e32 v131, v111
	v_add_f32_e32 v126, v164, v126
	v_exp_f32_e32 v132, v112
	v_add_f32_e32 v126, v165, v126
	v_exp_f32_e32 v133, v113
	v_add_f32_e32 v110, v130, v126
	v_exp_f32_e32 v134, v118
	v_add_f32_e32 v110, v131, v110
	v_exp_f32_e32 v135, v119
	v_exp_f32_e32 v102, v102
	v_add_f32_e32 v110, v132, v110
	v_exp_f32_e32 v103, v103
	v_add_f32_e32 v110, v133, v110
	v_exp_f32_e32 v104, v104
	v_add_f32_e32 v110, v134, v110
	v_exp_f32_e32 v105, v105
	v_add_f32_e32 v147, v135, v110
	v_add_f32_e32 v110, 0, v102
	v_exp_f32_e32 v168, v86
	v_add_f32_e32 v110, v103, v110
	v_exp_f32_e32 v169, v87
	v_add_f32_e32 v110, v104, v110
	v_exp_f32_e32 v170, v88
	v_add_f32_e32 v110, v105, v110
	v_exp_f32_e32 v171, v89
	v_add_f32_e32 v86, v168, v110
	v_exp_f32_e32 v172, v78
	v_add_f32_e32 v86, v169, v86
	v_exp_f32_e32 v173, v79
	v_add_f32_e32 v86, v170, v86
	v_exp_f32_e32 v174, v80
	v_add_f32_e32 v86, v171, v86
	v_exp_f32_e32 v175, v81
	v_add_f32_e32 v78, v172, v86
	v_exp_f32_e32 v176, v90
	v_add_f32_e32 v78, v173, v78
	v_exp_f32_e32 v177, v91
	v_add_f32_e32 v78, v174, v78
	v_exp_f32_e32 v178, v92
	v_add_f32_e32 v78, v175, v78
	v_exp_f32_e32 v179, v93
	v_add_f32_e32 v78, v176, v78
	v_exp_f32_e32 v86, v82
	v_add_f32_e32 v78, v177, v78
	v_exp_f32_e32 v87, v83
	v_add_f32_e32 v78, v178, v78
	v_exp_f32_e32 v88, v84
	v_add_f32_e32 v78, v179, v78
	v_exp_f32_e32 v89, v85
	v_add_f32_e32 v78, v86, v78
	v_exp_f32_e32 v90, v98
	v_add_f32_e32 v78, v87, v78
	v_exp_f32_e32 v91, v99
	v_exp_f32_e32 v127, v120
	v_add_f32_e32 v78, v88, v78
	v_exp_f32_e32 v126, v100
	v_exp_f32_e32 v129, v121
	v_add_f32_e32 v78, v89, v78
	v_exp_f32_e32 v128, v101
	v_exp_f32_e32 v111, v114
	v_add_f32_e32 v78, v90, v78
	v_exp_f32_e32 v110, v94
	v_exp_f32_e32 v115, v115
	v_add_f32_e32 v146, v91, v78
	v_exp_f32_e32 v114, v95
	v_exp_f32_e32 v113, v116
	v_exp_f32_e32 v112, v96
	v_pk_add_f32 v[78:79], v[126:127], v[146:147]
	v_exp_f32_e32 v119, v117
	v_exp_f32_e32 v118, v97
	v_pk_add_f32 v[78:79], v[128:129], v[78:79]
	v_exp_f32_e32 v117, v122
	v_exp_f32_e32 v116, v106
	v_pk_add_f32 v[78:79], v[110:111], v[78:79]
	v_exp_f32_e32 v123, v123
	v_exp_f32_e32 v122, v107
	v_pk_add_f32 v[78:79], v[114:115], v[78:79]
	v_exp_f32_e32 v121, v124
	v_exp_f32_e32 v120, v108
	v_pk_add_f32 v[78:79], v[112:113], v[78:79]
	v_exp_f32_e32 v125, v125
	v_exp_f32_e32 v124, v109
	v_pk_add_f32 v[78:79], v[118:119], v[78:79]
	v_pk_add_f32 v[78:79], v[116:117], v[78:79]
	v_cvt_pk_bf16_f32 v82, v148, v149
	v_pk_add_f32 v[78:79], v[122:123], v[78:79]
	v_cvt_pk_bf16_f32 v83, v150, v151
	v_pk_add_f32 v[78:79], v[120:121], v[78:79]
	v_cvt_pk_bf16_f32 v84, v152, v153
	v_pk_add_f32 v[78:79], v[124:125], v[78:79]
	v_cvt_pk_bf16_f32 v85, v166, v167
	v_pk_add_f32 v[156:157], v[156:157], v[78:79]
	v_cvt_pk_bf16_f32 v78, v102, v103
	v_cvt_pk_bf16_f32 v79, v104, v105
	v_cvt_pk_bf16_f32 v80, v168, v169
	v_cvt_pk_bf16_f32 v81, v170, v171
	ds_read_b64_tr_b16 v[204:205], v163 offset:37440
	ds_read_b64_tr_b16 v[206:207], v163 offset:39744
	s_waitcnt lgkmcnt(12)
	v_mfma_f32_16x16x32_bf16 v[62:65], v[180:183], v[82:85], v[62:65]
	v_lshl_add_u64 v[158:159], v[158:159], 0, s[36:37]
	v_lshl_add_u64 v[160:161], v[160:161], 0, s[14:15]
	v_mfma_f32_16x16x32_bf16 v[58:61], v[180:183], v[78:81], v[58:61]
	s_cmp_lg_u32 s27, s29
	ds_read_b64_tr_b16 v[180:181], v163 offset:37472
	ds_read_b64_tr_b16 v[182:183], v163 offset:39776
	s_waitcnt lgkmcnt(12)
	v_mfma_f32_16x16x32_bf16 v[70:73], v[184:187], v[82:85], v[70:73]
	v_mfma_f32_16x16x32_bf16 v[6:9], v[184:187], v[78:81], v[6:9]
	ds_read_b64_tr_b16 v[184:185], v163 offset:41984
	ds_read_b64_tr_b16 v[186:187], v163 offset:44288
	s_waitcnt lgkmcnt(12)
	v_mfma_f32_16x16x32_bf16 v[66:69], v[188:191], v[82:85], v[66:69]
	v_mfma_f32_16x16x32_bf16 v[10:13], v[188:191], v[78:81], v[10:13]
	ds_read_b64_tr_b16 v[188:189], v163 offset:42016
	ds_read_b64_tr_b16 v[190:191], v163 offset:44320
	s_waitcnt lgkmcnt(12)
; __device__ __forceinline__ unsigned cvt_pk_bf16(float lo, float hi) { const f32x2c f = {lo, hi}; return __builtin_bit_cast(unsigned, __builtin_convertvector(f, bf16x2c)); }
; #define LASP __attribute__((address_space(3)))
; template <int DQK>
; __device__ __forceinline__ void flash_item(unsigned char* smem, const bf16_t* Q, int qs, const bf16_t* K0, const bf16_t* V0, int n0, const bf16_t* K1, const bf16_t* V1, int n1, int ks, int vs, bf16_t* Oo, int os, float shift) {
;     ...
;         for (int kp = 0; kp < NKP; ++kp) {
;             bf16x8_t pb[2];
; #pragma unroll
;             for (int qg = 0; qg < 2; ++qg) {
;                 const f32x4_t a = s[2 * kp][qg], b = s[2 * kp + 1][qg];
;                 u32x4_t pk; pk.x = pg8::cvt_pk_bf16(a[0], a[1]); pk.y = pg8::cvt_pk_bf16(a[2], a[3]); pk.z = pg8::cvt_pk_bf16(b[0], b[1]); pk.w = pg8::cvt_pk_bf16(b[2], b[3]);
;                 pb[qg] = __builtin_bit_cast(bf16x8_t, pk);
;             }
; #pragma unroll
;             for (int dg = 0; dg < 4; ++dg) {
;                 LASP unsigned char* va = ls + VOFF + (32 * kp + 4 * fq + (fr >> 2)) * VR + (16 * dg + 4 * (fr & 3)) * 2;
;                 const s16x4 v0 = __builtin_amdgcn_ds_read_tr16_b64_v4i16((LASP s16x4*)va);
;                 const s16x4 v1 = __builtin_amdgcn_ds_read_tr16_b64_v4i16((LASP s16x4*)(va + 16 * VR));
;                 const bf16x8_t vf = __builtin_shufflevector(v0, v1, 0, 1, 2, 3, 4, 5, 6, 7);
;                 o[dg][0] = __builtin_amdgcn_mfma_f32_16x16x32_bf16(vf, pb[0], o[dg][0], 0, 0, 0);
;                 o[dg][1] = __builtin_amdgcn_mfma_f32_16x16x32_bf16(vf, pb[1], o[dg][1], 0, 0, 0);
;             }
;         }
	v_mfma_f32_16x16x32_bf16 v[74:77], v[192:195], v[82:85], v[74:77]
	v_cvt_pk_bf16_f32 v82, v172, v173
	v_cvt_pk_bf16_f32 v83, v174, v175
	v_cvt_pk_bf16_f32 v84, v176, v177
	v_mfma_f32_16x16x32_bf16 v[2:5], v[192:195], v[78:81], v[2:5]
	v_cvt_pk_bf16_f32 v78, v136, v137
	v_cvt_pk_bf16_f32 v79, v138, v139
	v_cvt_pk_bf16_f32 v80, v140, v141
	v_cvt_pk_bf16_f32 v81, v164, v165
	v_cvt_pk_bf16_f32 v85, v178, v179
	ds_read_b64_tr_b16 v[192:193], v163 offset:42048
	ds_read_b64_tr_b16 v[194:195], v163 offset:44352
	s_waitcnt lgkmcnt(12)
	v_mfma_f32_16x16x32_bf16 v[62:65], v[196:199], v[78:81], v[62:65]
	v_mfma_f32_16x16x32_bf16 v[58:61], v[196:199], v[82:85], v[58:61]
	ds_read_b64_tr_b16 v[196:197], v163 offset:42080
	ds_read_b64_tr_b16 v[198:199], v163 offset:44384
	s_waitcnt lgkmcnt(12)
	v_mfma_f32_16x16x32_bf16 v[74:77], v[200:203], v[78:81], v[74:77]
	v_mfma_f32_16x16x32_bf16 v[2:5], v[200:203], v[82:85], v[2:5]
	ds_read_b64_tr_b16 v[200:201], v163 offset:46592
	ds_read_b64_tr_b16 v[202:203], v163 offset:48896
	s_waitcnt lgkmcnt(12)
	v_mfma_f32_16x16x32_bf16 v[70:73], v[204:207], v[78:81], v[70:73]
	v_mfma_f32_16x16x32_bf16 v[6:9], v[204:207], v[82:85], v[6:9]
	ds_read_b64_tr_b16 v[204:205], v163 offset:46624
	ds_read_b64_tr_b16 v[206:207], v163 offset:48928
	s_waitcnt lgkmcnt(12)
	v_mfma_f32_16x16x32_bf16 v[10:13], v[180:183], v[82:85], v[10:13]
	v_cvt_pk_bf16_f32 v82, v86, v87
	v_cvt_pk_bf16_f32 v83, v88, v89
	v_mfma_f32_16x16x32_bf16 v[66:69], v[180:183], v[78:81], v[66:69]
	v_cvt_pk_bf16_f32 v78, v130, v131
	v_cvt_pk_bf16_f32 v79, v132, v133
	v_cvt_pk_bf16_f32 v80, v134, v135
	v_cvt_pk_bf16_f32 v81, v127, v129
	v_cvt_pk_bf16_f32 v84, v90, v91
	v_cvt_pk_bf16_f32 v85, v126, v128
	ds_read_b64_tr_b16 v[180:181], v163 offset:46656
	ds_read_b64_tr_b16 v[182:183], v163 offset:48960
	s_waitcnt lgkmcnt(12)
	v_mfma_f32_16x16x32_bf16 v[62:65], v[184:187], v[78:81], v[62:65]
	v_mfma_f32_16x16x32_bf16 v[58:61], v[184:187], v[82:85], v[58:61]
	ds_read_b64_tr_b16 v[184:185], v163 offset:46688
	ds_read_b64_tr_b16 v[186:187], v163 offset:48992
	s_waitcnt lgkmcnt(12)
	v_mfma_f32_16x16x32_bf16 v[74:77], v[188:191], v[78:81], v[74:77]
	v_mfma_f32_16x16x32_bf16 v[2:5], v[188:191], v[82:85], v[2:5]
	s_waitcnt lgkmcnt(10)
	v_mfma_f32_16x16x32_bf16 v[70:73], v[192:195], v[78:81], v[70:73]
	v_mfma_f32_16x16x32_bf16 v[6:9], v[192:195], v[82:85], v[6:9]
	s_waitcnt lgkmcnt(8)
	v_mfma_f32_16x16x32_bf16 v[66:69], v[196:199], v[78:81], v[66:69]
	v_cvt_pk_bf16_f32 v78, v111, v115
	v_cvt_pk_bf16_f32 v79, v113, v119
	v_cvt_pk_bf16_f32 v80, v117, v123
	v_mfma_f32_16x16x32_bf16 v[10:13], v[196:199], v[82:85], v[10:13]
	v_cvt_pk_bf16_f32 v81, v121, v125
	v_cvt_pk_bf16_f32 v82, v110, v114
	v_cvt_pk_bf16_f32 v83, v112, v118
	v_cvt_pk_bf16_f32 v84, v116, v122
	v_cvt_pk_bf16_f32 v85, v120, v124
	s_waitcnt lgkmcnt(6)
	v_mfma_f32_16x16x32_bf16 v[62:65], v[200:203], v[78:81], v[62:65]
	v_mfma_f32_16x16x32_bf16 v[58:61], v[200:203], v[82:85], v[58:61]
	s_waitcnt lgkmcnt(4)
	v_mfma_f32_16x16x32_bf16 v[74:77], v[204:207], v[78:81], v[74:77]
	v_mfma_f32_16x16x32_bf16 v[2:5], v[204:207], v[82:85], v[2:5]
	s_waitcnt lgkmcnt(2)
	v_mfma_f32_16x16x32_bf16 v[70:73], v[180:183], v[78:81], v[70:73]
	v_mfma_f32_16x16x32_bf16 v[6:9], v[180:183], v[82:85], v[6:9]
	s_waitcnt lgkmcnt(0)
	v_mfma_f32_16x16x32_bf16 v[66:69], v[184:187], v[78:81], v[66:69]
	v_mfma_f32_16x16x32_bf16 v[10:13], v[184:187], v[82:85], v[10:13]
	s_cbranch_scc0 .LBB0_834
; #define LASP __attribute__((address_space(3)))
; template <int DQK>
; __device__ __forceinline__ void flash_item(unsigned char* smem, const bf16_t* Q, int qs, const bf16_t* K0, const bf16_t* V0, int n0, const bf16_t* K1, const bf16_t* V1, int n1, int ks, int vs, bf16_t* Oo, int os, float shift) {
;     ...
;         __syncthreads();
; #pragma unroll
;         for (int c = 0; c < NKC; ++c) *(LASP u32x4_t*)(ls + (tid >> 2) * KR + ((tid & 3) + 4 * c) * 16) = kreg[c];
; #pragma unroll
;         for (int c = 0; c < NVC; ++c) *(LASP u32x4_t*)(ls + VOFF + ((tid >> 3) + 64 * c) * VR + (tid & 7) * 16) = vreg[c];
;         __syncthreads();
;         f32x4_t s[NKG][2];
; #pragma unroll
;         for (int kg = 0; kg < NKG; ++kg) { s[kg][0] = (f32x4_t){nsh, nsh, nsh, nsh}; s[kg][1] = (f32x4_t){nsh, nsh, nsh, nsh}; }
; #pragma unroll
;         for (int kk = 0; kk < NKK; ++kk) {
; #pragma unroll
;             for (int kg = 0; kg < NKG; ++kg) {
;                 const bf16x8_t kf = *(const LASP bf16x8_t*)(ls + (kg * 16 + fr) * KR + (kk * 32 + fq * 8) * 2);
;                 s[kg][0] = __builtin_amdgcn_mfma_f32_16x16x32_bf16(kf, qf[0][kk], s[kg][0], 0, 0, 0);
;                 s[kg][1] = __builtin_amdgcn_mfma_f32_16x16x32_bf16(kf, qf[1][kk], s[kg][1], 0, 0, 0);
;             }
;             asm volatile("" ::: "memory");
;         }
.LBB0_832:
	s_barrier
	s_waitcnt vmcnt(2)
	ds_write_b128 v1, v[42:45]
	ds_write_b128 v1, v[38:41] offset:64
	ds_write_b128 v1, v[46:49] offset:128
	s_waitcnt vmcnt(1)
	ds_write_b128 v143, v[50:53] offset:32768
	s_waitcnt vmcnt(0)
	ds_write_b128 v143, v[54:57] offset:41984
	s_waitcnt lgkmcnt(0)
	s_barrier
	ds_read_b128 v[180:183], v162
	ds_read_b128 v[184:187], v162 offset:3328
	ds_read_b128 v[188:191], v162 offset:6656
	ds_read_b128 v[192:195], v162 offset:9984
	ds_read_b128 v[196:199], v162 offset:13312
	ds_read_b128 v[200:203], v162 offset:16640
	ds_read_b128 v[204:207], v162 offset:19968
	ds_read_b128 v[212:215], v162 offset:23296
	ds_read_b128 v[224:227], v162 offset:64
	ds_read_b128 v[228:231], v162 offset:3392
	v_mov_b64_e32 v[84:85], s[46:47]
	v_mov_b64_e32 v[82:83], s[44:45]
	s_add_i32 s29, s29, 1
	s_cmp_ge_u32 s29, s27
	ds_read_b128 v[232:235], v162 offset:6720
	s_waitcnt lgkmcnt(10)
	v_mfma_f32_16x16x32_bf16 v[86:89], v[180:183], v[14:17], v[82:85]
	v_mfma_f32_16x16x32_bf16 v[78:81], v[180:183], v[18:21], v[82:85]
	ds_read_b128 v[180:183], v162 offset:10048
	s_waitcnt lgkmcnt(10)
	v_mfma_f32_16x16x32_bf16 v[94:97], v[184:187], v[14:17], v[82:85]
	v_mfma_f32_16x16x32_bf16 v[90:93], v[184:187], v[18:21], v[82:85]
	ds_read_b128 v[184:187], v162 offset:13376
	s_waitcnt lgkmcnt(10)
	v_mfma_f32_16x16x32_bf16 v[102:105], v[188:191], v[14:17], v[82:85]
	v_mfma_f32_16x16x32_bf16 v[98:101], v[188:191], v[18:21], v[82:85]
	ds_read_b128 v[188:191], v162 offset:16704
	s_waitcnt lgkmcnt(10)
	v_mfma_f32_16x16x32_bf16 v[110:113], v[192:195], v[14:17], v[82:85]
	v_mfma_f32_16x16x32_bf16 v[106:109], v[192:195], v[18:21], v[82:85]
	ds_read_b128 v[192:195], v162 offset:20032
	s_waitcnt lgkmcnt(10)
	v_mfma_f32_16x16x32_bf16 v[118:121], v[196:199], v[14:17], v[82:85]
	v_mfma_f32_16x16x32_bf16 v[114:117], v[196:199], v[18:21], v[82:85]
	ds_read_b128 v[196:199], v162 offset:23360
	s_waitcnt lgkmcnt(10)
	v_mfma_f32_16x16x32_bf16 v[126:129], v[200:203], v[14:17], v[82:85]
	v_mfma_f32_16x16x32_bf16 v[122:125], v[200:203], v[18:21], v[82:85]
	ds_read_b128 v[200:203], v162 offset:128
	s_waitcnt lgkmcnt(10)
	v_mfma_f32_16x16x32_bf16 v[134:137], v[204:207], v[14:17], v[82:85]
	v_mfma_f32_16x16x32_bf16 v[130:133], v[204:207], v[18:21], v[82:85]
	ds_read_b128 v[204:207], v162 offset:3456
	s_waitcnt lgkmcnt(10)
	v_mfma_f32_16x16x32_bf16 v[146:149], v[212:215], v[14:17], v[82:85]
	v_mfma_f32_16x16x32_bf16 v[82:85], v[212:215], v[18:21], v[82:85]
	ds_read_b128 v[212:215], v162 offset:10112
	s_waitcnt lgkmcnt(10)
	v_mfma_f32_16x16x32_bf16 v[86:89], v[224:227], v[22:25], v[86:89]
	v_mfma_f32_16x16x32_bf16 v[78:81], v[224:227], v[30:33], v[78:81]
	ds_read_b128 v[224:227], v162 offset:6784
	s_waitcnt lgkmcnt(10)
	v_mfma_f32_16x16x32_bf16 v[94:97], v[228:231], v[22:25], v[94:97]
	v_mfma_f32_16x16x32_bf16 v[90:93], v[228:231], v[30:33], v[90:93]
	ds_read_b128 v[228:231], v162 offset:13440
	s_waitcnt lgkmcnt(10)
	v_mfma_f32_16x16x32_bf16 v[150:153], v[232:235], v[22:25], v[102:105]
	s_nop 2
	ds_read_b128 v[236:239], v162 offset:16768
	s_waitcnt lgkmcnt(10)
	v_mfma_f32_16x16x32_bf16 v[110:113], v[180:183], v[22:25], v[110:113]
	v_mfma_f32_16x16x32_bf16 v[106:109], v[180:183], v[30:33], v[106:109]
	ds_read_b128 v[180:183], v162 offset:20096
	s_waitcnt lgkmcnt(10)
	v_mfma_f32_16x16x32_bf16 v[118:121], v[184:187], v[22:25], v[118:121]
	v_mfma_f32_16x16x32_bf16 v[114:117], v[184:187], v[30:33], v[114:117]
	ds_read_b128 v[184:187], v162 offset:23424
	s_waitcnt lgkmcnt(10)
	v_mfma_f32_16x16x32_bf16 v[164:167], v[188:191], v[22:25], v[126:129]
	v_mfma_f32_16x16x32_bf16 v[122:125], v[188:191], v[30:33], v[122:125]
	s_waitcnt lgkmcnt(9)
	v_mfma_f32_16x16x32_bf16 v[168:171], v[192:195], v[22:25], v[134:137]
	v_mfma_f32_16x16x32_bf16 v[172:175], v[192:195], v[30:33], v[130:133]
	s_waitcnt lgkmcnt(8)
	v_mfma_f32_16x16x32_bf16 v[176:179], v[196:199], v[30:33], v[82:85]
	s_nop 2
	v_mfma_f32_16x16x32_bf16 v[98:101], v[232:235], v[30:33], v[98:101]
	v_mfma_f32_16x16x32_bf16 v[146:149], v[196:199], v[22:25], v[146:149]
	s_waitcnt lgkmcnt(7)
	v_mfma_f32_16x16x32_bf16 v[138:141], v[200:203], v[34:37], v[86:89]
	v_mfma_f32_16x16x32_bf16 v[102:105], v[200:203], v[26:29], v[78:81]
	s_nop 1
	s_waitcnt lgkmcnt(6)
	v_mfma_f32_16x16x32_bf16 v[134:137], v[204:207], v[34:37], v[94:97]
	s_nop 2
	v_mfma_f32_16x16x32_bf16 v[86:89], v[204:207], v[26:29], v[90:93]
	s_waitcnt lgkmcnt(5)
	v_mfma_f32_16x16x32_bf16 v[126:129], v[212:215], v[34:37], v[110:113]
	v_mfma_f32_16x16x32_bf16 v[90:93], v[212:215], v[26:29], v[106:109]
	s_waitcnt lgkmcnt(4)
	v_mfma_f32_16x16x32_bf16 v[130:133], v[224:227], v[34:37], v[150:153]
	v_mfma_f32_16x16x32_bf16 v[78:81], v[224:227], v[26:29], v[98:101]
	s_waitcnt lgkmcnt(3)
	v_mfma_f32_16x16x32_bf16 v[110:113], v[228:231], v[34:37], v[118:121]
	s_waitcnt lgkmcnt(2)
	v_mfma_f32_16x16x32_bf16 v[118:121], v[236:239], v[34:37], v[164:167]
	v_mfma_f32_16x16x32_bf16 v[98:101], v[236:239], v[26:29], v[122:125]
	v_mfma_f32_16x16x32_bf16 v[82:85], v[228:231], v[26:29], v[114:117]
	s_waitcnt lgkmcnt(1)
	v_mfma_f32_16x16x32_bf16 v[114:117], v[180:183], v[34:37], v[168:171]
	v_mfma_f32_16x16x32_bf16 v[94:97], v[180:183], v[26:29], v[172:175]
	s_waitcnt lgkmcnt(0)
	v_mfma_f32_16x16x32_bf16 v[122:125], v[184:187], v[34:37], v[146:149]
	v_mfma_f32_16x16x32_bf16 v[106:109], v[184:187], v[26:29], v[176:179]
	s_cbranch_scc1 .LBB0_831
	v_lshl_add_u64 v[54:55], s[56:57], 0, v[158:159]
	v_add_co_u32_e32 v50, vcc, 0x1bc98000, v54
	v_lshl_add_u64 v[46:47], s[56:57], 0, v[160:161]
	s_nop 0
	v_addc_co_u32_e32 v51, vcc, 0, v55, vcc
	v_add_co_u32_e32 v54, vcc, 0x1bca4000, v54
	global_load_dwordx4 v[42:45], v[46:47], off offset:-64
	global_load_dwordx4 v[38:41], v[46:47], off
	v_addc_co_u32_e32 v55, vcc, 0, v55, vcc
	global_load_dwordx4 v[46:49], v[46:47], off offset:64
	s_nop 0
	global_load_dwordx4 v[50:53], v[50:51], off
	s_nop 0
	global_load_dwordx4 v[54:57], v[54:55], off
	s_branch .LBB0_831

; #define LASP __attribute__((address_space(3)))
; __device__ __forceinline__ void na_item(unsigned char* smem, const bf16_t* U, const float* rpb_l, bf16_t* O, int b, int rp, int hp, float shift) {
;     ...
;         f32x4_t sA[4], sB[4];
; #pragma unroll
;         for (int g = 0; g < 4; ++g) { sA[g] = (f32x4_t){nsh, nsh, nsh, nsh}; sB[g] = (f32x4_t){nsh, nsh, nsh, nsh}; }
; #pragma unroll
;         for (int kk = 0; kk < 2; ++kk) {
; #pragma unroll
;             for (int g = 0; g < 2; ++g) {
;                 const bf16x8_t kl = *(const LASP bf16x8_t*)(base + (kcol0 + 16 * g + fr) * KR + (kk * 32 + fq * 8) * 2);
;                 sA[g] = __builtin_amdgcn_mfma_f32_16x16x32_bf16(kl, qfA[kk], sA[g], 0, 0, 0);
;                 sB[g] = __builtin_amdgcn_mfma_f32_16x16x32_bf16(kl, qfB[kk], sB[g], 0, 0, 0);
;                 const bf16x8_t kc = *(const LASP bf16x8_t*)(base + O_KC + (16 * g + fr) * KR + (kk * 32 + fq * 8) * 2);
;                 sA[2 + g] = __builtin_amdgcn_mfma_f32_16x16x32_bf16(kc, qfA[kk], sA[2 + g], 0, 0, 0);
;                 sB[2 + g] = __builtin_amdgcn_mfma_f32_16x16x32_bf16(kc, qfB[kk], sB[2 + g], 0, 0, 0);
;             }
;         }
;         const int relA = rsA + i - rA + 7, relB = relA - 1;
;         const int brA = min(max(relA, 0), 14), brB = min(max(relB, 0), 14);
; #pragma unroll
;         for (int g = 0; g < 2; ++g)
; #pragma unroll
;             for (int j = 0; j < 4; ++j) {
;                 const int kc = kcol0 + 16 * g + 4 * fq + j;
;                 const bool valid = (kc >= cs) && (kc < cs + 16);
;                 const int idx = min(max(kc - qc + 15, 0), 30);
;                 sA[g][j] = (valid && latA) ? sA[g][j] + bias[(hh * 15 + brA) * 32 + idx] : -INFINITY;
;                 sB[g][j] = (valid && latB) ? sB[g][j] + bias[(hh * 15 + brB) * 32 + idx] : -INFINITY;
;             }
.LBB0_859:
	s_bitcmp1_b32 s78, 0
	s_cselect_b32 s18, 0xd800, 0
	v_add_u32_e32 v111, s18, v121
	v_add_u32_e32 v86, v111, v108
	v_add_u32_e32 v144, v86, v126
	ds_read_b128 v[164:167], v144 offset:2304
	ds_read_b128 v[168:171], v144
	v_mov_b64_e32 v[80:81], s[62:63]
	v_mov_b64_e32 v[78:79], s[60:61]
	v_add_u32_e32 v145, v86, v127
	ds_read_b128 v[172:175], v145 offset:18432
	ds_read_b128 v[176:179], v145 offset:20736
	ds_read_b128 v[200:203], v144 offset:64
	ds_read_b128 v[204:207], v145 offset:18496
	s_cmp_lt_u32 s78, 8
	s_cselect_b64 vcc, -1, 0
	s_add_i32 s79, s97, s78
	ds_read_b128 v[212:215], v144 offset:2368
	s_waitcnt lgkmcnt(6)
	v_mfma_f32_16x16x32_bf16 v[136:139], v[164:167], v[14:17], v[78:81]
	s_max_i32 s18, s79, -7
	s_add_i32 s18, s18, 7
	s_min_u32 s18, s18, 14
	v_mfma_f32_16x16x32_bf16 v[140:143], v[164:167], v[22:25], v[78:81]
	ds_read_b128 v[164:167], v145 offset:20800
	s_waitcnt lgkmcnt(6)
	v_mfma_f32_16x16x32_bf16 v[82:85], v[168:171], v[14:17], v[78:81]
	v_mfma_f32_16x16x32_bf16 v[74:77], v[168:171], v[22:25], v[78:81]
	s_waitcnt lgkmcnt(5)
	v_mfma_f32_16x16x32_bf16 v[90:93], v[172:175], v[14:17], v[78:81]
	v_mfma_f32_16x16x32_bf16 v[86:89], v[172:175], v[22:25], v[78:81]
	s_waitcnt lgkmcnt(4)
	v_mfma_f32_16x16x32_bf16 v[156:159], v[176:179], v[14:17], v[78:81]
	v_mfma_f32_16x16x32_bf16 v[160:163], v[176:179], v[22:25], v[78:81]
	s_nop 2
	s_waitcnt lgkmcnt(3)
	v_mfma_f32_16x16x32_bf16 v[102:105], v[200:203], v[18:21], v[82:85]
	s_nop 2
	v_mfma_f32_16x16x32_bf16 v[98:101], v[200:203], v[26:29], v[74:77]
	s_waitcnt lgkmcnt(2)
	v_mfma_f32_16x16x32_bf16 v[74:77], v[204:207], v[18:21], v[90:93]
	v_mfma_f32_16x16x32_bf16 v[78:81], v[204:207], v[26:29], v[86:89]
	s_nop 2
	s_waitcnt lgkmcnt(1)
	v_mfma_f32_16x16x32_bf16 v[94:97], v[212:215], v[18:21], v[136:139]
	v_mfma_f32_16x16x32_bf16 v[90:93], v[212:215], v[26:29], v[140:143]
	s_nop 1
	v_add_u32_e32 v136, s18, v122
	v_lshl_add_u32 v138, v136, 7, s4
	s_waitcnt lgkmcnt(0)
	v_mfma_f32_16x16x32_bf16 v[82:85], v[164:167], v[18:21], v[156:159]
	s_cmp_ge_i32 s78, s5
	s_cselect_b64 s[76:77], -1, 0
	s_max_i32 s18, s79, -6
	s_add_i32 s18, s18, 6
	s_min_u32 s18, s18, 14
	v_mfma_f32_16x16x32_bf16 v[86:89], v[164:167], v[26:29], v[160:163]
	v_add_u32_e32 v139, s18, v122
	v_lshl_add_u32 v139, v139, 7, s4
	v_lshl_add_u32 v196, v128, 2, v138
	ds_read_b32 v180, v196
	v_lshl_add_u32 v197, v128, 2, v139
	ds_read_b32 v181, v197
	v_lshl_add_u32 v196, v129, 2, v138
	ds_read_b32 v182, v196
	v_lshl_add_u32 v197, v129, 2, v139
	ds_read_b32 v183, v197
	v_lshl_add_u32 v196, v130, 2, v138
	ds_read_b32 v184, v196
	v_lshl_add_u32 v197, v130, 2, v139
	ds_read_b32 v185, v197
	v_lshl_add_u32 v196, v131, 2, v138
	ds_read_b32 v186, v196
	v_lshl_add_u32 v197, v131, 2, v139
	ds_read_b32 v187, v197
	v_lshl_add_u32 v196, v132, 2, v138
	ds_read_b32 v188, v196
	v_lshl_add_u32 v197, v132, 2, v139
	ds_read_b32 v189, v197
	v_lshl_add_u32 v196, v133, 2, v138
	ds_read_b32 v190, v196
	v_lshl_add_u32 v197, v133, 2, v139
	ds_read_b32 v191, v197
	v_lshl_add_u32 v196, v134, 2, v138
	ds_read_b32 v192, v196
	v_lshl_add_u32 v197, v134, 2, v139
	ds_read_b32 v193, v197
	s_waitcnt lgkmcnt(12)
	s_and_b64 s[18:19], s[20:21], vcc
	v_add_f32_e32 v180, v102, v180
	v_cndmask_b32_e64 v137, v154, v180, s[18:19]
	s_and_b64 s[18:19], s[20:21], s[76:77]
	v_add_f32_e32 v181, v98, v181
	v_cndmask_b32_e64 v136, v154, v181, s[18:19]
	v_lshl_add_u32 v196, v135, 2, v138
	ds_read_b32 v194, v196
	v_lshl_add_u32 v197, v135, 2, v139
	ds_read_b32 v195, v197
	s_waitcnt lgkmcnt(12)
	s_and_b64 s[18:19], s[40:41], vcc
	v_add_f32_e32 v182, v103, v182
	v_cndmask_b32_e64 v102, v154, v182, s[18:19]
	s_and_b64 s[18:19], s[40:41], s[76:77]
	v_add_f32_e32 v183, v99, v183
	v_cndmask_b32_e64 v98, v154, v183, s[18:19]
	s_waitcnt lgkmcnt(10)
	s_and_b64 s[18:19], s[16:17], vcc
	v_add_f32_e32 v184, v104, v184
	v_cndmask_b32_e64 v103, v154, v184, s[18:19]
	s_and_b64 s[18:19], s[16:17], s[76:77]
	v_add_f32_e32 v185, v100, v185
	v_cndmask_b32_e64 v99, v154, v185, s[18:19]
	s_waitcnt lgkmcnt(8)
	s_and_b64 s[18:19], s[2:3], vcc
	v_add_f32_e32 v186, v105, v186
	v_cndmask_b32_e64 v104, v154, v186, s[18:19]
	s_and_b64 s[18:19], s[2:3], s[76:77]
	v_add_f32_e32 v187, v101, v187
	v_cndmask_b32_e64 v100, v154, v187, s[18:19]
	s_waitcnt lgkmcnt(6)
	s_and_b64 s[18:19], s[26:27], vcc
	v_add_f32_e32 v188, v94, v188
	v_cndmask_b32_e64 v105, v154, v188, s[18:19]
	s_and_b64 s[18:19], s[26:27], s[76:77]
	v_add_f32_e32 v189, v90, v189
	v_cndmask_b32_e64 v101, v154, v189, s[18:19]
	s_waitcnt lgkmcnt(4)
	s_and_b64 s[18:19], s[74:75], vcc
	v_add_f32_e32 v190, v95, v190
	v_cndmask_b32_e64 v140, v154, v190, s[18:19]
	s_and_b64 s[18:19], s[74:75], s[76:77]
	v_add_f32_e32 v191, v91, v191
	v_cndmask_b32_e64 v94, v154, v191, s[18:19]
	s_waitcnt lgkmcnt(2)
	s_and_b64 s[18:19], s[52:53], vcc
	v_add_f32_e32 v192, v96, v192
	v_cndmask_b32_e64 v91, v154, v192, s[18:19]
	s_and_b64 s[18:19], s[52:53], s[76:77]
	v_add_f32_e32 v193, v92, v193
	v_cndmask_b32_e64 v90, v154, v193, s[18:19]
	s_waitcnt lgkmcnt(0)
; #define LASP __attribute__((address_space(3)))
; __device__ __forceinline__ void na_item(unsigned char* smem, const bf16_t* U, const float* rpb_l, bf16_t* O, int b, int rp, int hp, float shift) {
;     ...
;                 sA[g][j] = (valid && latA) ? sA[g][j] + bias[(hh * 15 + brA) * 32 + idx] : -INFINITY;
;                 sB[g][j] = (valid && latB) ? sB[g][j] + bias[(hh * 15 + brB) * 32 + idx] : -INFINITY;
;             }
;         if (!hasctx) {
; #pragma unroll
;             for (int g = 2; g < 4; ++g) { sA[g] = (f32x4_t){-INFINITY, -INFINITY, -INFINITY, -INFINITY}; sB[g] = sA[g]; }
;         }
;         { float psA = 0.f, psB = 0.f;
; #pragma unroll
;           for (int g = 0; g < 4; ++g)
; #pragma unroll
;               for (int j = 0; j < 4; ++j) { const float pa = __builtin_amdgcn_exp2f(sA[g][j]); sA[g][j] = pa; psA += pa;
;                                             const float pb_ = __builtin_amdgcn_exp2f(sB[g][j]); sB[g][j] = pb_; psB += pb_; }
;           lA += psA; lB += psB; }
; #pragma unroll
;         for (int kp = 0; kp < 2; ++kp) {
;             u32x4_t pk;
;             pk.x = pg8::cvt_pk_bf16(sA[2 * kp][0], sA[2 * kp][1]); pk.y = pg8::cvt_pk_bf16(sA[2 * kp][2], sA[2 * kp][3]); pk.z = pg8::cvt_pk_bf16(sA[2 * kp + 1][0], sA[2 * kp + 1][1]); pk.w = pg8::cvt_pk_bf16(sA[2 * kp + 1][2], sA[2 * kp + 1][3]);
;             const bf16x8_t pbA = __builtin_bit_cast(bf16x8_t, pk);
;             pk.x = pg8::cvt_pk_bf16(sB[2 * kp][0], sB[2 * kp][1]); pk.y = pg8::cvt_pk_bf16(sB[2 * kp][2], sB[2 * kp][3]); pk.z = pg8::cvt_pk_bf16(sB[2 * kp + 1][0], sB[2 * kp + 1][1]); pk.w = pg8::cvt_pk_bf16(sB[2 * kp + 1][2], sB[2 * kp + 1][3]);
;             const bf16x8_t pbB = __builtin_bit_cast(bf16x8_t, pk);
;             LASP unsigned char* vb = kp == 0 ? base + O_VL + (kcol0 + 4 * fq + (fr >> 2)) * KR : base + O_VC + (4 * fq + (fr >> 2)) * KR;
; #pragma unroll
;             for (int dg = 0; dg < 4; ++dg) {
;                 LASP unsigned char* va = vb + (16 * dg + 4 * (fr & 3)) * 2;
;                 const s16x4 v0 = __builtin_amdgcn_ds_read_tr16_b64_v4i16((LASP s16x4*)va);
;                 const s16x4 v1 = __builtin_amdgcn_ds_read_tr16_b64_v4i16((LASP s16x4*)(va + 16 * KR));
;                 const bf16x8_t vf = __builtin_shufflevector(v0, v1, 0, 1, 2, 3, 4, 5, 6, 7);
;                 oA[dg] = __builtin_amdgcn_mfma_f32_16x16x32_bf16(vf, pbA, oA[dg], 0, 0, 0);
	s_and_b64 s[18:19], s[38:39], vcc
	v_add_f32_e32 v194, v97, v194
	v_cndmask_b32_e64 v96, v154, v194, s[18:19]
	s_and_b64 s[18:19], s[38:39], s[76:77]
	v_add_f32_e32 v195, v93, v195
	v_cndmask_b32_e64 v92, v154, v195, s[18:19]
	s_mov_b64 s[76:77], exec
	s_mov_b64 s[78:79], exec
	v_add3_u32 v198, v111, v125, v123
	ds_read_b64_tr_b16 v[166:167], v198 offset:11520
	ds_read_b64_tr_b16 v[164:165], v198 offset:9216
	ds_read_b64_tr_b16 v[168:169], v198 offset:9280
	ds_read_b64_tr_b16 v[170:171], v198 offset:11584
	ds_read_b64_tr_b16 v[172:173], v198 offset:9248
	ds_read_b64_tr_b16 v[174:175], v198 offset:11552
	ds_read_b64_tr_b16 v[176:177], v198 offset:9312
	ds_read_b64_tr_b16 v[178:179], v198 offset:11616
	v_add3_u32 v199, v111, v124, v123
	ds_read_b64_tr_b16 v[182:183], v199 offset:25344
	ds_read_b64_tr_b16 v[180:181], v199 offset:23040
	ds_read_b64_tr_b16 v[184:185], v199 offset:23104
	ds_read_b64_tr_b16 v[186:187], v199 offset:25408
	v_exp_f32_e32 v137, v137
	v_exp_f32_e32 v136, v136
	v_exp_f32_e32 v139, v102
	v_exp_f32_e32 v138, v98
	v_exp_f32_e32 v103, v103
	v_exp_f32_e32 v102, v99
	v_exp_f32_e32 v143, v104
	v_exp_f32_e32 v142, v100
	v_cndmask_b32_e32 v148, v154, v84, vcc
	v_cndmask_b32_e32 v149, v154, v83, vcc
	v_cndmask_b32_e32 v83, v154, v75, vcc
	v_cndmask_b32_e32 v84, v154, v74, vcc
	v_exp_f32_e32 v105, v105
	v_exp_f32_e32 v104, v101
	v_exp_f32_e32 v141, v140
	v_exp_f32_e32 v140, v94
	v_pk_add_f32 v[74:75], v[136:137], 0 op_sel_hi:[1,0]
	v_exp_f32_e32 v95, v91
	v_pk_add_f32 v[74:75], v[138:139], v[74:75]
	v_exp_f32_e32 v94, v90
	v_pk_add_f32 v[74:75], v[102:103], v[74:75]
	v_exp_f32_e32 v93, v96
	v_pk_add_f32 v[74:75], v[142:143], v[74:75]
	v_exp_f32_e32 v92, v92
	v_pk_add_f32 v[74:75], v[104:105], v[74:75]
	v_cvt_pk_bf16_f32 v101, v102, v142
	v_cvt_pk_bf16_f32 v102, v104, v140
	v_pk_add_f32 v[74:75], v[140:141], v[74:75]
	v_cvt_pk_bf16_f32 v96, v137, v139
	v_cvt_pk_bf16_f32 v98, v105, v141
	v_cvt_pk_bf16_f32 v100, v136, v138
	v_cndmask_b32_e32 v97, v154, v89, vcc
	v_cndmask_b32_e32 v76, v154, v76, vcc
	v_cndmask_b32_e32 v145, v154, v87, vcc
	v_exp_f32_e32 v87, v76
	v_exp_f32_e32 v76, v97
	v_cvt_pk_bf16_f32 v97, v103, v143
	v_cvt_pk_bf16_f32 v99, v95, v93
	v_cvt_pk_bf16_f32 v103, v94, v92
	ds_read_b64_tr_b16 v[188:189], v199 offset:23072
	ds_read_b64_tr_b16 v[190:191], v199 offset:25376
	s_waitcnt lgkmcnt(12)
	v_mfma_f32_16x16x32_bf16 v[70:73], v[164:167], v[96:99], v[70:73]
	v_cndmask_b32_e32 v144, v154, v88, vcc
	v_cndmask_b32_e32 v146, v154, v86, vcc
	v_cndmask_b32_e32 v81, v154, v81, vcc
	v_mfma_f32_16x16x32_bf16 v[54:57], v[164:167], v[100:103], v[54:57]
	v_cndmask_b32_e32 v80, v154, v80, vcc
	v_cndmask_b32_e32 v79, v154, v79, vcc
	ds_read_b64_tr_b16 v[164:165], v199 offset:23136
	ds_read_b64_tr_b16 v[166:167], v199 offset:25440
	s_waitcnt lgkmcnt(12)
	v_mfma_f32_16x16x32_bf16 v[62:65], v[168:171], v[96:99], v[62:65]
	v_cndmask_b32_e32 v78, v154, v78, vcc
	v_cndmask_b32_e32 v147, v154, v85, vcc
	v_cndmask_b32_e32 v82, v154, v82, vcc
	v_mfma_f32_16x16x32_bf16 v[6:9], v[168:171], v[100:103], v[6:9]
	v_cndmask_b32_e32 v77, v154, v77, vcc
	v_exp_f32_e32 v91, v84
	v_exp_f32_e32 v90, v78
	v_exp_f32_e32 v89, v83
	v_exp_f32_e32 v88, v79
	v_exp_f32_e32 v86, v80
	v_exp_f32_e32 v85, v77
	v_exp_f32_e32 v84, v81
	v_exp_f32_e32 v83, v82
	v_exp_f32_e32 v82, v146
	v_exp_f32_e32 v81, v149
	v_exp_f32_e32 v80, v145
	v_exp_f32_e32 v79, v148
	v_exp_f32_e32 v78, v144
	v_exp_f32_e32 v77, v147
	s_waitcnt lgkmcnt(10)
	v_mfma_f32_16x16x32_bf16 v[66:69], v[172:175], v[96:99], v[66:69]
	v_add_f32_e64 v74, v94, v74
	v_add_f32_e64 v75, v95, v75
	v_lshl_add_u64 v[114:115], v[114:115], 0, s[14:15]
	v_pk_add_f32 v[74:75], v[92:93], v[74:75]
	v_mfma_f32_16x16x32_bf16 v[2:5], v[172:175], v[100:103], v[2:5]
	v_add_f32_e64 v74, v90, v74
	v_add_f32_e64 v75, v91, v75
	v_lshl_add_u64 v[116:117], v[116:117], 0, s[34:35]
	v_pk_add_f32 v[74:75], v[88:89], v[74:75]
	s_waitcnt lgkmcnt(8)
	v_mfma_f32_16x16x32_bf16 v[58:61], v[176:179], v[96:99], v[58:61]
	v_cvt_pk_bf16_f32 v96, v91, v89
	v_cvt_pk_bf16_f32 v97, v87, v85
	v_cvt_pk_bf16_f32 v98, v83, v81
	v_mfma_f32_16x16x32_bf16 v[10:13], v[176:179], v[100:103], v[10:13]
	v_cvt_pk_bf16_f32 v99, v79, v77
	v_cvt_pk_bf16_f32 v100, v90, v88
	v_cvt_pk_bf16_f32 v101, v86, v84
	v_cvt_pk_bf16_f32 v102, v82, v80
	v_cvt_pk_bf16_f32 v103, v78, v76
	s_waitcnt lgkmcnt(6)
	v_mfma_f32_16x16x32_bf16 v[70:73], v[180:183], v[96:99], v[70:73]
	v_pk_add_f32 v[74:75], v[86:87], v[74:75]
	s_andn2_b64 vcc, exec, s[28:29]
	v_mfma_f32_16x16x32_bf16 v[54:57], v[180:183], v[100:103], v[54:57]
	v_pk_add_f32 v[74:75], v[84:85], v[74:75]
	s_waitcnt lgkmcnt(4)
	v_mfma_f32_16x16x32_bf16 v[62:65], v[184:187], v[96:99], v[62:65]
	v_add_f32_e64 v74, v82, v74
	v_add_f32_e64 v75, v83, v75
	v_pk_add_f32 v[74:75], v[80:81], v[74:75]
	v_mfma_f32_16x16x32_bf16 v[6:9], v[184:187], v[100:103], v[6:9]
	v_pk_add_f32 v[74:75], v[78:79], v[74:75]
	s_waitcnt lgkmcnt(2)
	v_mfma_f32_16x16x32_bf16 v[66:69], v[188:191], v[96:99], v[66:69]
	v_add_f32_e64 v74, v76, v74
	v_add_f32_e64 v75, v77, v75
	s_waitcnt lgkmcnt(0)
	s_barrier
	v_pk_add_f32 v[112:113], v[112:113], v[74:75]
	v_mfma_f32_16x16x32_bf16 v[2:5], v[188:191], v[100:103], v[2:5]
	v_mfma_f32_16x16x32_bf16 v[58:61], v[164:167], v[96:99], v[58:61]
	v_mfma_f32_16x16x32_bf16 v[10:13], v[164:167], v[100:103], v[10:13]
	s_cbranch_vccz .LBB0_819
	s_mov_b32 s78, s54
	s_branch .LBB0_848
